# v6 + dil: lane reductions via DPP adds / permlane swaps instead of 40 ds_bpermute round trips per item
# speedup vs baseline: 1.0153x; 1.0052x over previous
; #define LAS __attribute__((address_space(3)))
; __device__ __forceinline__ float bf2f(unsigned h) { return __uint_as_float(h << 16); }
; __device__ __forceinline__ unsigned pk2(float lo, float hi) { return pg8::cvt_pk_bf16(lo, hi); }
; __device__ __forceinline__ void da_blk_stage(const Ctx& X, const f32x4 g0, const f32x4 g1, int kb, const DaBlk& R) {
;     const lptr KN = X.lds + DA_KN, VT = X.lds + DA_VT; const int slot = ((kb % 3) + 3) % 3;
; #pragma unroll
;     for (int p = 0; p < 2; ++p) { const int row = slot * 64 + (X.tid >> 4) + 32 * p, c8 = X.tid & 15; const v4u kw = R.kw[p], vw = R.vw[p];
;         float f[8]; f[0] = bf2f(kw.x & 0xffffu); f[1] = bf2f(kw.x >> 16); f[2] = bf2f(kw.y & 0xffffu); f[3] = bf2f(kw.y >> 16); f[4] = bf2f(kw.z & 0xffffu); f[5] = bf2f(kw.z >> 16); f[6] = bf2f(kw.w & 0xffffu); f[7] = bf2f(kw.w >> 16);
;         float s = 0.f;
; #pragma unroll
;         for (int e = 0; e < 8; ++e) s += f[e] * f[e];
;         s += __shfl_xor(s, 1); s += __shfl_xor(s, 2); s += __shfl_xor(s, 4); s += __shfl_xor(s, 8);
;         const float sc = __builtin_amdgcn_rsqf(s * (1.0f / 128.0f) + EPS);
;         v4u o; o.x = pk2(f[0] * sc * g0.x, f[1] * sc * g0.y); o.y = pk2(f[2] * sc * g0.z, f[3] * sc * g0.w); o.z = pk2(f[4] * sc * g1.x, f[5] * sc * g1.y); o.w = pk2(f[6] * sc * g1.z, f[7] * sc * g1.w);
;         *(LAS v4u*)(KN + row * 272 + c8 * 16) = o;
;         LAS unsigned short* d = (LAS unsigned short*)(VT + (8 * c8) * 400 + (row ^ (8 * (c8 & 7))) * 2);
;         d[0] = (unsigned short)vw.x; d[200] = (unsigned short)(vw.x >> 16); d[400] = (unsigned short)vw.y; d[600] = (unsigned short)(vw.y >> 16);
;         d[800] = (unsigned short)vw.z; d[1000] = (unsigned short)(vw.z >> 16); d[1200] = (unsigned short)vw.w; d[1400] = (unsigned short)(vw.w >> 16); }
; __device__ __forceinline__ void dil_run(const Ctx& X, bf16* H, int l, int run) {
;     ...
;         da_blk_stage(X, kg0, kg1, I.nb0 - 1, B0); da_blk_stage(X, kg0, kg1, I.nb0, B1); da_blk_stage(X, kg0, kg1, I.nb0 + 1, B2);
.LBB0_268:
	s_or_b64 exec, exec, s[22:23]
	s_waitcnt vmcnt(0)
	v_lshlrev_b32_e32 v70, 16, v54
	v_and_b32_e32 v71, 0xffff0000, v54
	v_lshlrev_b32_e32 v66, 16, v55
	v_and_b32_e32 v67, 0xffff0000, v55
	v_pk_mul_f32 v[54:55], v[70:71], v[70:71]
	v_pk_mul_f32 v[68:69], v[66:67], v[66:67]
	v_add_f32_e32 v54, v54, v55
	v_lshlrev_b32_e32 v64, 16, v56
	v_and_b32_e32 v65, 0xffff0000, v56
	v_add_f32_e32 v54, v68, v54
	v_and_b32_e32 v58, 64, v195
	v_lshlrev_b32_e32 v60, 16, v57
	v_and_b32_e32 v61, 0xffff0000, v57
	v_pk_mul_f32 v[56:57], v[64:65], v[64:65]
	v_add_f32_e32 v54, v69, v54
	v_xor_b32_e32 v59, 1, v195
	v_add_u32_e32 v58, 64, v58
	v_add_f32_e32 v54, v56, v54
	v_cmp_lt_i32_e32 vcc, v59, v58
	v_pk_mul_f32 v[62:63], v[60:61], v[60:61]
	v_add_f32_e32 v54, v57, v54
	v_cndmask_b32_e32 v59, v195, v59, vcc
	v_add_f32_e32 v54, v62, v54
	v_lshlrev_b32_e32 v156, 2, v59
	v_add_f32_e32 v54, v63, v54
	v_xor_b32_e32 v59, 2, v195
	v_cmp_lt_i32_e32 vcc, v59, v58
	s_lshr_b32 s52, s52, 5
	s_and_b64 s[0:1], s[0:1], exec
	v_cndmask_b32_e32 v59, v195, v59, vcc
	v_lshlrev_b32_e32 v157, 2, v59
	s_waitcnt lgkmcnt(0)
	s_nop 1
	v_add_f32_dpp v54, v54, v54 quad_perm:[1,0,3,2] row_mask:0xf bank_mask:0xf
	v_xor_b32_e32 v59, 4, v195
	v_cmp_lt_i32_e32 vcc, v59, v58
	s_cselect_b32 s22, 1, -1
	s_and_b64 s[0:1], s[4:5], exec
	v_cndmask_b32_e32 v59, v195, v59, vcc
	v_lshlrev_b32_e32 v158, 2, v59
	s_waitcnt lgkmcnt(0)
	s_nop 1
	v_add_f32_dpp v54, v54, v54 quad_perm:[2,3,0,1] row_mask:0xf bank_mask:0xf
	v_xor_b32_e32 v59, 8, v195
	v_cmp_lt_i32_e32 vcc, v59, v58
	s_movk_i32 s0, 0x800
	s_cselect_b32 s13, s0, 0x200
	v_cndmask_b32_e32 v59, v195, v59, vcc
	v_lshlrev_b32_e32 v161, 2, v59
	s_waitcnt lgkmcnt(0)
	s_nop 1
	v_add_f32_dpp v54, v54, v54 row_half_mirror row_mask:0xf bank_mask:0xf
	s_and_b64 s[0:1], s[16:17], exec
	s_mul_hi_i32 s0, s55, 0x55555556
	s_cselect_b32 s23, 0x2000, s13
	s_lshr_b32 s1, s0, 31
	s_waitcnt lgkmcnt(0)
	s_nop 1
	v_add_f32_dpp v54, v54, v54 row_mirror row_mask:0xf bank_mask:0xf
	v_fmamk_f32 v54, v54, 0x3c000000, v1
	s_add_i32 s0, s0, s1
	v_rsq_f32_e32 v62, v54
	s_mul_i32 s0, s0, 3
	s_sub_i32 s0, s55, s0
	s_lshl_b32 s1, s0, 6
	s_add_i32 s13, s1, 0xc0
	v_pk_mul_f32 v[54:55], v[62:63], v[70:71] op_sel_hi:[0,1]
	v_pk_mul_f32 v[56:57], v[62:63], v[66:67] op_sel_hi:[0,1]
	s_cmp_lt_i32 s0, 0
	v_pk_mul_f32 v[54:55], v[2:3], v[54:55]
	v_pk_mul_f32 v[56:57], v[4:5], v[56:57]
	s_cselect_b32 s0, s13, s1
	v_cvt_pk_bf16_f32 v54, v54, v55
	v_cvt_pk_bf16_f32 v55, v56, v57
	v_pk_mul_f32 v[56:57], v[62:63], v[64:65] op_sel_hi:[0,1]
	v_pk_mul_f32 v[60:61], v[62:63], v[60:61] op_sel_hi:[0,1]
	v_add_u32_e32 v59, s0, v129
	v_pk_mul_f32 v[56:57], v[6:7], v[56:57]
	v_pk_mul_f32 v[60:61], v[8:9], v[60:61]
	v_cvt_pk_bf16_f32 v56, v56, v57
	v_cvt_pk_bf16_f32 v57, v60, v61
	v_mad_u64_u32 v[60:61], s[0:1], v59, s27, v[112:113]
	v_lshlrev_b32_e32 v64, 16, v46
	v_and_b32_e32 v65, 0xffff0000, v46
	ds_write_b128 v60, v[54:57]
	v_xor_b32_e32 v54, v59, v132
	v_lshlrev_b32_e32 v56, 16, v47
	v_and_b32_e32 v57, 0xffff0000, v47
	v_pk_mul_f32 v[46:47], v[64:65], v[64:65]
	v_lshl_add_u32 v54, v54, 1, v131
	v_pk_mul_f32 v[62:63], v[56:57], v[56:57]
	v_add_f32_e32 v46, v46, v47
	ds_write_b16 v54, v50 offset:52224
	ds_write_b16_d16_hi v54, v50 offset:52624
	ds_write_b16 v54, v51 offset:53024
	ds_write_b16_d16_hi v54, v51 offset:53424
	ds_write_b16 v54, v52 offset:53824
	ds_write_b16_d16_hi v54, v52 offset:54224
	ds_write_b16 v54, v53 offset:54624
	ds_write_b16_d16_hi v54, v53 offset:55024
	v_lshlrev_b32_e32 v54, 16, v48
	v_and_b32_e32 v55, 0xffff0000, v48
	v_add_f32_e32 v46, v62, v46
	v_lshlrev_b32_e32 v50, 16, v49
	v_and_b32_e32 v51, 0xffff0000, v49
	v_pk_mul_f32 v[48:49], v[54:55], v[54:55]
	v_add_f32_e32 v46, v63, v46
	v_add_f32_e32 v46, v48, v46
	v_pk_mul_f32 v[52:53], v[50:51], v[50:51]
	v_add_f32_e32 v46, v49, v46
	v_add_f32_e32 v46, v52, v46
	v_add_f32_e32 v46, v53, v46
	v_add_u32_e32 v59, 32, v59
	s_mul_hi_i32 s0, s15, 0x55555556
	s_lshr_b32 s1, s0, 31
	s_add_i32 s0, s0, s1
	s_waitcnt lgkmcnt(0)
	s_nop 1
	v_add_f32_dpp v46, v46, v46 quad_perm:[1,0,3,2] row_mask:0xf bank_mask:0xf
	s_mul_i32 s0, s0, 3
	s_sub_i32 s0, s15, s0
	s_lshl_b32 s1, s0, 6
	s_add_i32 s13, s1, 0xc0
	s_waitcnt lgkmcnt(0)
	s_nop 1
	v_add_f32_dpp v46, v46, v46 quad_perm:[2,3,0,1] row_mask:0xf bank_mask:0xf
	s_cmp_lt_i32 s0, 0
	s_cselect_b32 s0, s13, s1
	v_mov_b32_e32 v119, v159
	s_mov_b32 s30, 0
	s_waitcnt lgkmcnt(0)
	s_nop 1
	v_add_f32_dpp v46, v46, v46 row_half_mirror row_mask:0xf bank_mask:0xf
	s_mov_b32 s31, 4
	s_waitcnt lgkmcnt(0)
	s_nop 1
	v_add_f32_dpp v46, v46, v46 row_mirror row_mask:0xf bank_mask:0xf
	v_fmamk_f32 v46, v46, 0x3c000000, v1
	v_rsq_f32_e32 v52, v46
	s_nop 0
	v_pk_mul_f32 v[46:47], v[52:53], v[64:65] op_sel_hi:[0,1]
	v_pk_mul_f32 v[48:49], v[52:53], v[56:57] op_sel_hi:[0,1]
	v_pk_mul_f32 v[46:47], v[2:3], v[46:47]
	v_pk_mul_f32 v[48:49], v[4:5], v[48:49]
	v_cvt_pk_bf16_f32 v46, v46, v47
	v_cvt_pk_bf16_f32 v47, v48, v49
	v_pk_mul_f32 v[48:49], v[52:53], v[54:55] op_sel_hi:[0,1]
	v_pk_mul_f32 v[50:51], v[52:53], v[50:51] op_sel_hi:[0,1]
	v_pk_mul_f32 v[48:49], v[6:7], v[48:49]
	v_pk_mul_f32 v[50:51], v[8:9], v[50:51]
	v_cvt_pk_bf16_f32 v48, v48, v49
	v_cvt_pk_bf16_f32 v49, v50, v51
	v_lshlrev_b32_e32 v52, 16, v42
	v_and_b32_e32 v53, 0xffff0000, v42
	ds_write_b128 v60, v[46:49] offset:8704
	v_xor_b32_e32 v46, v59, v132
	v_lshlrev_b32_e32 v48, 16, v43
	v_and_b32_e32 v49, 0xffff0000, v43
	v_pk_mul_f32 v[42:43], v[52:53], v[52:53]
	v_lshl_add_u32 v46, v46, 1, v131
	v_pk_mul_f32 v[50:51], v[48:49], v[48:49]
	v_add_f32_e32 v42, v42, v43
	ds_write_b16 v46, v38 offset:52224
	ds_write_b16_d16_hi v46, v38 offset:52624
	ds_write_b16 v46, v39 offset:53024
	ds_write_b16_d16_hi v46, v39 offset:53424
	ds_write_b16 v46, v40 offset:53824
	ds_write_b16_d16_hi v46, v40 offset:54224
	ds_write_b16 v46, v41 offset:54624
	ds_write_b16_d16_hi v46, v41 offset:55024
	v_lshlrev_b32_e32 v40, 16, v44
	v_and_b32_e32 v41, 0xffff0000, v44
	v_add_f32_e32 v42, v50, v42
	v_lshlrev_b32_e32 v46, 16, v45
	v_and_b32_e32 v47, 0xffff0000, v45
	v_pk_mul_f32 v[44:45], v[40:41], v[40:41]
	v_add_f32_e32 v42, v51, v42
	v_add_f32_e32 v42, v44, v42
	v_pk_mul_f32 v[38:39], v[46:47], v[46:47]
	v_add_f32_e32 v42, v45, v42
	v_add_f32_e32 v38, v38, v42
	v_add_f32_e32 v38, v39, v38
	v_add_u32_e32 v54, s0, v129
	s_waitcnt lgkmcnt(0)
; #define LAS __attribute__((address_space(3)))
; __device__ __forceinline__ float bf2f(unsigned h) { return __uint_as_float(h << 16); }
; __device__ __forceinline__ unsigned pk2(float lo, float hi) { return pg8::cvt_pk_bf16(lo, hi); }
; __device__ __forceinline__ void da_blk_stage(const Ctx& X, const f32x4 g0, const f32x4 g1, int kb, const DaBlk& R) {
;     const lptr KN = X.lds + DA_KN, VT = X.lds + DA_VT; const int slot = ((kb % 3) + 3) % 3;
; #pragma unroll
;     for (int p = 0; p < 2; ++p) { const int row = slot * 64 + (X.tid >> 4) + 32 * p, c8 = X.tid & 15; const v4u kw = R.kw[p], vw = R.vw[p];
;         float f[8]; f[0] = bf2f(kw.x & 0xffffu); f[1] = bf2f(kw.x >> 16); f[2] = bf2f(kw.y & 0xffffu); f[3] = bf2f(kw.y >> 16); f[4] = bf2f(kw.z & 0xffffu); f[5] = bf2f(kw.z >> 16); f[6] = bf2f(kw.w & 0xffffu); f[7] = bf2f(kw.w >> 16);
;         float s = 0.f;
; #pragma unroll
;         for (int e = 0; e < 8; ++e) s += f[e] * f[e];
;         s += __shfl_xor(s, 1); s += __shfl_xor(s, 2); s += __shfl_xor(s, 4); s += __shfl_xor(s, 8);
;         const float sc = __builtin_amdgcn_rsqf(s * (1.0f / 128.0f) + EPS);
;         v4u o; o.x = pk2(f[0] * sc * g0.x, f[1] * sc * g0.y); o.y = pk2(f[2] * sc * g0.z, f[3] * sc * g0.w); o.z = pk2(f[4] * sc * g1.x, f[5] * sc * g1.y); o.w = pk2(f[6] * sc * g1.z, f[7] * sc * g1.w);
;         *(LAS v4u*)(KN + row * 272 + c8 * 16) = o;
;         LAS unsigned short* d = (LAS unsigned short*)(VT + (8 * c8) * 400 + (row ^ (8 * (c8 & 7))) * 2);
;         d[0] = (unsigned short)vw.x; d[200] = (unsigned short)(vw.x >> 16); d[400] = (unsigned short)vw.y; d[600] = (unsigned short)(vw.y >> 16);
;         d[800] = (unsigned short)vw.z; d[1000] = (unsigned short)(vw.z >> 16); d[1200] = (unsigned short)vw.w; d[1400] = (unsigned short)(vw.w >> 16); }
	s_nop 1
	v_add_f32_dpp v38, v38, v38 quad_perm:[1,0,3,2] row_mask:0xf bank_mask:0xf
	s_waitcnt lgkmcnt(0)
	s_nop 1
	v_add_f32_dpp v38, v38, v38 quad_perm:[2,3,0,1] row_mask:0xf bank_mask:0xf
	s_waitcnt lgkmcnt(0)
	s_nop 1
	v_add_f32_dpp v38, v38, v38 row_half_mirror row_mask:0xf bank_mask:0xf
	s_waitcnt lgkmcnt(0)
	s_nop 1
	v_add_f32_dpp v38, v38, v38 row_mirror row_mask:0xf bank_mask:0xf
	v_fmamk_f32 v38, v38, 0x3c000000, v1
	v_rsq_f32_e32 v42, v38
	s_nop 0
	v_pk_mul_f32 v[38:39], v[42:43], v[52:53] op_sel_hi:[0,1]
	v_pk_mul_f32 v[44:45], v[42:43], v[48:49] op_sel_hi:[0,1]
	v_pk_mul_f32 v[40:41], v[42:43], v[40:41] op_sel_hi:[0,1]
	v_pk_mul_f32 v[42:43], v[42:43], v[46:47] op_sel_hi:[0,1]
	v_pk_mul_f32 v[38:39], v[2:3], v[38:39]
	v_pk_mul_f32 v[44:45], v[4:5], v[44:45]
	v_pk_mul_f32 v[40:41], v[6:7], v[40:41]
	v_pk_mul_f32 v[42:43], v[8:9], v[42:43]
	v_cvt_pk_bf16_f32 v38, v38, v39
	v_cvt_pk_bf16_f32 v39, v44, v45
	v_cvt_pk_bf16_f32 v40, v40, v41
	v_cvt_pk_bf16_f32 v41, v42, v43
	v_mad_u64_u32 v[42:43], s[0:1], v54, s27, v[112:113]
	v_lshlrev_b32_e32 v46, 16, v30
	v_and_b32_e32 v47, 0xffff0000, v30
	ds_write_b128 v42, v[38:41]
	v_xor_b32_e32 v38, v54, v132
	v_lshlrev_b32_e32 v40, 16, v31
	v_and_b32_e32 v41, 0xffff0000, v31
	v_pk_mul_f32 v[30:31], v[46:47], v[46:47]
	v_lshl_add_u32 v38, v38, 1, v131
	v_pk_mul_f32 v[44:45], v[40:41], v[40:41]
	v_add_f32_e32 v30, v30, v31
	ds_write_b16 v38, v34 offset:52224
	ds_write_b16_d16_hi v38, v34 offset:52624
	ds_write_b16 v38, v35 offset:53024
	ds_write_b16_d16_hi v38, v35 offset:53424
	ds_write_b16 v38, v36 offset:53824
	ds_write_b16_d16_hi v38, v36 offset:54224
	ds_write_b16 v38, v37 offset:54624
	ds_write_b16_d16_hi v38, v37 offset:55024
	v_lshlrev_b32_e32 v38, 16, v32
	v_and_b32_e32 v39, 0xffff0000, v32
	v_add_f32_e32 v30, v44, v30
	v_lshlrev_b32_e32 v34, 16, v33
	v_and_b32_e32 v35, 0xffff0000, v33
	v_pk_mul_f32 v[32:33], v[38:39], v[38:39]
	v_add_f32_e32 v30, v45, v30
	v_add_f32_e32 v30, v32, v30
	v_pk_mul_f32 v[36:37], v[34:35], v[34:35]
	v_add_f32_e32 v30, v33, v30
	v_add_f32_e32 v30, v36, v30
	v_add_f32_e32 v30, v37, v30
	v_add_u32_e32 v43, 32, v54
	s_mul_hi_i32 s0, s53, 0x55555556
	s_lshr_b32 s1, s0, 31
	s_add_i32 s0, s0, s1
	s_waitcnt lgkmcnt(0)
	s_nop 1
	v_add_f32_dpp v30, v30, v30 quad_perm:[1,0,3,2] row_mask:0xf bank_mask:0xf
	s_mul_i32 s0, s0, 3
	s_sub_i32 s0, s53, s0
	s_lshl_b32 s1, s0, 6
	s_add_i32 s13, s1, 0xc0
	s_waitcnt lgkmcnt(0)
	s_nop 1
	v_add_f32_dpp v30, v30, v30 quad_perm:[2,3,0,1] row_mask:0xf bank_mask:0xf
	s_cmp_lt_i32 s0, 0
	s_cselect_b32 s0, s13, s1
	s_ashr_i32 s13, s12, 31
	s_waitcnt lgkmcnt(0)
	s_nop 1
	v_add_f32_dpp v30, v30, v30 row_half_mirror row_mask:0xf bank_mask:0xf
	s_waitcnt lgkmcnt(0)
	s_nop 1
	v_add_f32_dpp v30, v30, v30 row_mirror row_mask:0xf bank_mask:0xf
	v_fmamk_f32 v30, v30, 0x3c000000, v1
	v_rsq_f32_e32 v36, v30
	s_nop 0
	v_pk_mul_f32 v[30:31], v[36:37], v[46:47] op_sel_hi:[0,1]
	v_pk_mul_f32 v[32:33], v[36:37], v[40:41] op_sel_hi:[0,1]
	v_pk_mul_f32 v[30:31], v[2:3], v[30:31]
	v_pk_mul_f32 v[32:33], v[4:5], v[32:33]
	v_cvt_pk_bf16_f32 v30, v30, v31
	v_cvt_pk_bf16_f32 v31, v32, v33
	v_pk_mul_f32 v[32:33], v[36:37], v[38:39] op_sel_hi:[0,1]
	v_pk_mul_f32 v[34:35], v[36:37], v[34:35] op_sel_hi:[0,1]
	v_pk_mul_f32 v[32:33], v[6:7], v[32:33]
	v_pk_mul_f32 v[34:35], v[8:9], v[34:35]
	v_cvt_pk_bf16_f32 v32, v32, v33
	v_cvt_pk_bf16_f32 v33, v34, v35
	v_lshlrev_b32_e32 v36, 16, v26
	v_and_b32_e32 v37, 0xffff0000, v26
	ds_write_b128 v42, v[30:33] offset:8704
	v_xor_b32_e32 v30, v43, v132
	v_lshlrev_b32_e32 v32, 16, v27
	v_and_b32_e32 v33, 0xffff0000, v27
	v_pk_mul_f32 v[26:27], v[36:37], v[36:37]
	v_lshl_add_u32 v30, v30, 1, v131
	v_pk_mul_f32 v[34:35], v[32:33], v[32:33]
	v_add_f32_e32 v26, v26, v27
	ds_write_b16 v30, v22 offset:52224
	ds_write_b16_d16_hi v30, v22 offset:52624
	ds_write_b16 v30, v23 offset:53024
	ds_write_b16_d16_hi v30, v23 offset:53424
	ds_write_b16 v30, v24 offset:53824
	ds_write_b16_d16_hi v30, v24 offset:54224
	ds_write_b16 v30, v25 offset:54624
	ds_write_b16_d16_hi v30, v25 offset:55024
	v_lshlrev_b32_e32 v24, 16, v28
	v_and_b32_e32 v25, 0xffff0000, v28
	v_add_f32_e32 v26, v34, v26
	v_lshlrev_b32_e32 v30, 16, v29
	v_and_b32_e32 v31, 0xffff0000, v29
	v_pk_mul_f32 v[28:29], v[24:25], v[24:25]
	v_add_f32_e32 v26, v35, v26
	v_add_f32_e32 v26, v28, v26
	v_pk_mul_f32 v[22:23], v[30:31], v[30:31]
	v_add_f32_e32 v26, v29, v26
	v_add_f32_e32 v22, v22, v26
	v_add_f32_e32 v22, v23, v22
	v_add_u32_e32 v38, s0, v129
	s_and_b64 s[0:1], s[4:5], exec
	s_cselect_b32 s4, 11, 9
	s_and_b64 s[0:1], s[16:17], exec
	s_waitcnt lgkmcnt(0)
	s_nop 1
	v_add_f32_dpp v22, v22, v22 quad_perm:[1,0,3,2] row_mask:0xf bank_mask:0xf
	v_xor_b32_e32 v42, 16, v195
	v_cmp_lt_i32_e32 vcc, v42, v58
	s_waitcnt lgkmcnt(0)
	s_nop 1
	v_add_f32_dpp v22, v22, v22 quad_perm:[2,3,0,1] row_mask:0xf bank_mask:0xf
	v_cndmask_b32_e32 v42, v195, v42, vcc
	v_lshlrev_b32_e32 v166, 2, v42
	v_xor_b32_e32 v42, 32, v195
	v_cmp_lt_i32_e32 vcc, v42, v58
	s_waitcnt lgkmcnt(0)
	s_nop 1
	v_add_f32_dpp v22, v22, v22 row_half_mirror row_mask:0xf bank_mask:0xf
	v_cndmask_b32_e32 v42, v195, v42, vcc
	v_lshlrev_b32_e32 v167, 2, v42
	v_mov_b32_e32 v42, s52
	v_bfe_i32 v42, v42, 0, 8
	s_waitcnt lgkmcnt(0)
; #define LAS __attribute__((address_space(3)))
; __device__ __forceinline__ float bf2f(unsigned h) { return __uint_as_float(h << 16); }
; __device__ __forceinline__ unsigned pk2(float lo, float hi) { return pg8::cvt_pk_bf16(lo, hi); }
; __device__ __forceinline__ void da_blk_stage(const Ctx& X, const f32x4 g0, const f32x4 g1, int kb, const DaBlk& R) {
;     const lptr KN = X.lds + DA_KN, VT = X.lds + DA_VT; const int slot = ((kb % 3) + 3) % 3;
; #pragma unroll
;     for (int p = 0; p < 2; ++p) { const int row = slot * 64 + (X.tid >> 4) + 32 * p, c8 = X.tid & 15; const v4u kw = R.kw[p], vw = R.vw[p];
;         float f[8]; f[0] = bf2f(kw.x & 0xffffu); f[1] = bf2f(kw.x >> 16); f[2] = bf2f(kw.y & 0xffffu); f[3] = bf2f(kw.y >> 16); f[4] = bf2f(kw.z & 0xffffu); f[5] = bf2f(kw.z >> 16); f[6] = bf2f(kw.w & 0xffffu); f[7] = bf2f(kw.w >> 16);
;         float s = 0.f;
; #pragma unroll
;         for (int e = 0; e < 8; ++e) s += f[e] * f[e];
;         s += __shfl_xor(s, 1); s += __shfl_xor(s, 2); s += __shfl_xor(s, 4); s += __shfl_xor(s, 8);
;         const float sc = __builtin_amdgcn_rsqf(s * (1.0f / 128.0f) + EPS);
;         v4u o; o.x = pk2(f[0] * sc * g0.x, f[1] * sc * g0.y); o.y = pk2(f[2] * sc * g0.z, f[3] * sc * g0.w); o.z = pk2(f[4] * sc * g1.x, f[5] * sc * g1.y); o.w = pk2(f[6] * sc * g1.z, f[7] * sc * g1.w);
;         *(LAS v4u*)(KN + row * 272 + c8 * 16) = o;
;         LAS unsigned short* d = (LAS unsigned short*)(VT + (8 * c8) * 400 + (row ^ (8 * (c8 & 7))) * 2);
;         d[0] = (unsigned short)vw.x; d[200] = (unsigned short)(vw.x >> 16); d[400] = (unsigned short)vw.y; d[600] = (unsigned short)(vw.y >> 16);
;         d[800] = (unsigned short)vw.z; d[1000] = (unsigned short)(vw.z >> 16); d[1200] = (unsigned short)vw.w; d[1400] = (unsigned short)(vw.w >> 16); }
; __device__ __forceinline__ void da_q_load(const Ctx& X, const bf16* H, const DaRun& I, int nb, v4u (&qw)[2][4]) {
;     const int fr = X.lane & 15, fq = X.lane >> 4, qh = X.wave & 1;
; #pragma unroll
;     for (int u = 0; u < 2; ++u) { const size_t m = (size_t)I.b * SEQ + (size_t)(I.rho * (SEQ / I.dil) + 64 * nb + 32 * qh + 16 * u + fr);
; #pragma unroll
;         for (int ks = 0; ks < 4; ++ks) qw[u][ks] = *(const v4u*)hptr(H, m, I.qcol + 32 * ks + 8 * fq); }
	s_nop 1
	v_add_f32_dpp v22, v22, v22 row_mirror row_mask:0xf bank_mask:0xf
	v_fmamk_f32 v22, v22, 0x3c000000, v1
	v_rsq_f32_e32 v26, v22
	v_ashrrev_i32_e32 v43, 31, v42
	v_lshlrev_b64 v[42:43], 2, v[42:43]
	v_lshl_add_u64 v[124:125], s[28:29], 0, v[42:43]
	v_pk_mul_f32 v[22:23], v[26:27], v[36:37] op_sel_hi:[0,1]
	v_pk_mul_f32 v[28:29], v[26:27], v[32:33] op_sel_hi:[0,1]
	v_pk_mul_f32 v[24:25], v[26:27], v[24:25] op_sel_hi:[0,1]
	v_pk_mul_f32 v[26:27], v[26:27], v[30:31] op_sel_hi:[0,1]
	v_pk_mul_f32 v[22:23], v[2:3], v[22:23]
	v_pk_mul_f32 v[28:29], v[4:5], v[28:29]
	v_pk_mul_f32 v[24:25], v[6:7], v[24:25]
	v_pk_mul_f32 v[26:27], v[8:9], v[26:27]
	v_cvt_pk_bf16_f32 v22, v22, v23
	v_cvt_pk_bf16_f32 v23, v28, v29
	v_cvt_pk_bf16_f32 v24, v24, v25
	v_cvt_pk_bf16_f32 v25, v26, v27
	v_mad_u64_u32 v[26:27], s[0:1], v38, s27, v[112:113]
	v_lshlrev_b32_e32 v30, 16, v10
	v_and_b32_e32 v31, 0xffff0000, v10
	ds_write_b128 v26, v[22:25]
	v_xor_b32_e32 v22, v38, v132
	v_lshlrev_b32_e32 v24, 16, v11
	v_and_b32_e32 v25, 0xffff0000, v11
	v_pk_mul_f32 v[10:11], v[30:31], v[30:31]
	v_lshl_add_u32 v22, v22, 1, v131
	v_pk_mul_f32 v[28:29], v[24:25], v[24:25]
	v_add_f32_e32 v10, v10, v11
	ds_write_b16 v22, v18 offset:52224
	ds_write_b16_d16_hi v22, v18 offset:52624
	ds_write_b16 v22, v19 offset:53024
	ds_write_b16_d16_hi v22, v19 offset:53424
	ds_write_b16 v22, v20 offset:53824
	ds_write_b16_d16_hi v22, v20 offset:54224
	ds_write_b16 v22, v21 offset:54624
	ds_write_b16_d16_hi v22, v21 offset:55024
	v_lshlrev_b32_e32 v22, 16, v12
	v_and_b32_e32 v23, 0xffff0000, v12
	v_add_f32_e32 v10, v28, v10
	v_lshlrev_b32_e32 v18, 16, v13
	v_and_b32_e32 v19, 0xffff0000, v13
	v_pk_mul_f32 v[12:13], v[22:23], v[22:23]
	v_add_f32_e32 v10, v29, v10
	v_add_f32_e32 v10, v12, v10
	v_pk_mul_f32 v[20:21], v[18:19], v[18:19]
	v_add_f32_e32 v10, v13, v10
	v_add_f32_e32 v10, v20, v10
	v_add_f32_e32 v10, v21, v10
	v_add_u32_e32 v27, 32, v38
	s_cselect_b32 s0, 13, s4
	s_lshl_b32 s53, s70, s0
	s_lshl_b64 s[4:5], s[12:13], 21
	s_waitcnt lgkmcnt(0)
	s_nop 1
	v_add_f32_dpp v10, v10, v10 quad_perm:[1,0,3,2] row_mask:0xf bank_mask:0xf
	s_add_u32 s0, s36, s4
	s_addc_u32 s1, s37, s5
	s_lshr_b32 s34, s51, 7
	s_lshl_b64 s[16:17], s[34:35], 22
	s_waitcnt lgkmcnt(0)
	s_nop 1
	v_add_f32_dpp v10, v10, v10 quad_perm:[2,3,0,1] row_mask:0xf bank_mask:0xf
	s_add_i32 s34, s51, 0x200
	s_lshr_b32 s34, s34, 7
	s_lshl_b64 s[54:55], s[34:35], 22
	s_lshl_b32 s71, s22, 1
	s_waitcnt lgkmcnt(0)
	s_nop 1
	v_add_f32_dpp v10, v10, v10 row_half_mirror row_mask:0xf bank_mask:0xf
	s_lshl_b64 s[58:59], s[12:13], 13
	v_add_u32_e32 v42, s53, v129
	v_lshl_add_u64 v[120:121], v[116:117], 0, s[54:55]
	s_waitcnt lgkmcnt(0)
	s_nop 1
	v_add_f32_dpp v10, v10, v10 row_mirror row_mask:0xf bank_mask:0xf
	v_fmamk_f32 v10, v10, 0x3c000000, v1
	v_rsq_f32_e32 v20, v10
	s_nop 0
	v_pk_mul_f32 v[10:11], v[20:21], v[30:31] op_sel_hi:[0,1]
	v_pk_mul_f32 v[12:13], v[20:21], v[24:25] op_sel_hi:[0,1]
	v_pk_mul_f32 v[10:11], v[2:3], v[10:11]
	v_pk_mul_f32 v[12:13], v[4:5], v[12:13]
	v_cvt_pk_bf16_f32 v10, v10, v11
	v_cvt_pk_bf16_f32 v11, v12, v13
	v_pk_mul_f32 v[12:13], v[20:21], v[22:23] op_sel_hi:[0,1]
	v_pk_mul_f32 v[18:19], v[20:21], v[18:19] op_sel_hi:[0,1]
	v_pk_mul_f32 v[12:13], v[6:7], v[12:13]
	v_pk_mul_f32 v[18:19], v[8:9], v[18:19]
	v_cvt_pk_bf16_f32 v12, v12, v13
	v_cvt_pk_bf16_f32 v13, v18, v19
	ds_write_b128 v26, v[10:13] offset:8704
	v_xor_b32_e32 v10, v27, v132
	v_lshl_add_u32 v10, v10, 1, v131
	ds_write_b16 v10, v14 offset:52224
	ds_write_b16_d16_hi v10, v14 offset:52624
	ds_write_b16 v10, v15 offset:53024
	ds_write_b16_d16_hi v10, v15 offset:53424
	ds_write_b16 v10, v16 offset:53824
	ds_write_b16_d16_hi v10, v16 offset:54224
	ds_write_b16 v10, v17 offset:54624
	ds_write_b16_d16_hi v10, v17 offset:55024
	v_lshl_or_b32 v10, s15, 6, v133
	v_add_u32_e32 v26, s53, v10
	v_ashrrev_i32_e32 v27, 31, v26
	v_lshlrev_b64 v[10:11], 8, v[26:27]
	v_add_u32_e32 v26, 16, v26
	v_ashrrev_i32_e32 v27, 31, v26
	v_lshlrev_b64 v[26:27], 8, v[26:27]
	v_lshl_add_u64 v[10:11], s[0:1], 0, v[10:11]
	v_lshl_add_u64 v[26:27], s[0:1], 0, v[26:27]
	v_lshl_add_u64 v[10:11], v[10:11], 0, s[16:17]
	v_lshl_add_u64 v[26:27], v[26:27], 0, s[16:17]
	v_lshl_add_u64 v[22:23], v[10:11], 0, v[118:119]
	v_lshl_add_u64 v[38:39], v[26:27], 0, v[118:119]
	global_load_dwordx4 v[10:13], v[22:23], off
	global_load_dwordx4 v[14:17], v[22:23], off offset:64
	global_load_dwordx4 v[18:21], v[22:23], off offset:128
	s_nop 0
	global_load_dwordx4 v[22:25], v[22:23], off offset:192
	s_nop 0
	global_load_dwordx4 v[26:29], v[38:39], off
	global_load_dwordx4 v[30:33], v[38:39], off offset:64
	global_load_dwordx4 v[34:37], v[38:39], off offset:128
	s_nop 0
	global_load_dwordx4 v[38:41], v[38:39], off offset:192
	s_add_i32 s15, s51, 0x400
	s_lshr_b32 s34, s15, 7
	s_ashr_i32 s15, s14, 31
	s_lshl_b64 s[56:57], s[34:35], 22
	s_add_i32 s34, s69, -1
	s_lshl_b64 s[14:15], s[14:15], 14
	s_add_u32 s12, s14, s58
	s_addc_u32 s13, s15, s59
	s_lshl_b32 s14, s51, 7
	s_and_b32 s14, s14, 0x1fc000
	s_add_u32 s14, s58, s14
	s_addc_u32 s15, s59, 0
	s_add_u32 s0, s0, s16
	s_addc_u32 s1, s1, s17
	s_add_i32 s75, s49, s50
	v_lshl_add_u64 v[126:127], s[0:1], 0, v[118:119]
	s_add_i32 s0, s75, s22
	s_lshl_b32 s0, s0, 6
	s_add_i32 s0, s0, s53
	v_or_b32_e32 v119, s0, v133
	s_add_i32 s0, s75, s71
	v_lshl_add_u32 v168, s0, 6, v42
	s_lshl_b32 s0, s48, 8
	s_lshl_b32 s1, s49, 6
	s_waitcnt lgkmcnt(0)
	s_barrier
	s_or_b32 s77, s0, s1
	s_add_i32 s0, s77, s53
	v_lshl_add_u64 v[122:123], v[116:117], 0, s[56:57]
	s_lshl_b32 s76, s22, 6
	v_or_b32_e32 v169, s77, v128
	v_add_u32_e32 v170, s0, v148
	v_add_u32_e32 v171, s77, v42
	v_add_u32_e32 v172, s77, v134
	s_add_i32 s78, s77, s21
	s_branch .LBB0_270

; #define LAS __attribute__((address_space(3)))
; __device__ __forceinline__ float bf2f(unsigned h) { return __uint_as_float(h << 16); }
; __device__ __forceinline__ unsigned pk2(float lo, float hi) { return pg8::cvt_pk_bf16(lo, hi); }
; __device__ __forceinline__ void dil_run(const Ctx& X, bf16* H, int l, int run) {
;     ...
;         for (int u = 0; u < 2; ++u) {
;             float s = 0.f;
; #pragma unroll
;             for (int ks = 0; ks < 4; ++ks) { const v4u qw = qw_[u][ks];
;                 const float a0 = bf2f(qw.x & 0xffffu), a1 = bf2f(qw.x >> 16), a2 = bf2f(qw.y & 0xffffu), a3 = bf2f(qw.y >> 16), a4 = bf2f(qw.z & 0xffffu), a5 = bf2f(qw.z >> 16), a6 = bf2f(qw.w & 0xffffu), a7 = bf2f(qw.w >> 16);
;                 s += (a0 * a0 + a1 * a1) + (a2 * a2 + a3 * a3) + (a4 * a4 + a5 * a5) + (a6 * a6 + a7 * a7); }
;             s += __shfl_xor(s, 16); s += __shfl_xor(s, 32);
;             const float sc = (0.08838834764831845f * 1.4426950408889634f) * __builtin_amdgcn_rsqf(s * (1.0f / 128.0f) + EPS);
; #pragma unroll
;             for (int ks = 0; ks < 4; ++ks) { const v4u qw = qw_[u][ks]; const f32x4 g0 = *(const LAS f32x4*)(qgl + 32 * ks + 8 * fq), g1 = *(const LAS f32x4*)(qgl + 32 * ks + 8 * fq + 4);
;                 v4u o; o.x = pk2(bf2f(qw.x & 0xffffu) * sc * g0.x, bf2f(qw.x >> 16) * sc * g0.y); o.y = pk2(bf2f(qw.y & 0xffffu) * sc * g0.z, bf2f(qw.y >> 16) * sc * g0.w);
;                 o.z = pk2(bf2f(qw.z & 0xffffu) * sc * g1.x, bf2f(qw.z >> 16) * sc * g1.y); o.w = pk2(bf2f(qw.w & 0xffffu) * sc * g1.z, bf2f(qw.w >> 16) * sc * g1.w);
;                 qf[u][ks] = __builtin_bit_cast(bf16x8, o); }
;         }
.LBB0_270:
	s_waitcnt vmcnt(6)
	v_and_b32_e32 v177, 0xffff0000, v17
	v_and_b32_e32 v179, 0xffff0000, v16
	v_lshlrev_b32_e32 v176, 16, v17
	v_lshlrev_b32_e32 v178, 16, v16
	v_mov_b32_e32 v182, v177
	v_mov_b32_e32 v183, v179
	v_mov_b32_e32 v180, v176
	v_mov_b32_e32 v181, v178
	v_pk_mul_f32 v[182:183], v[182:183], v[182:183]
	v_and_b32_e32 v185, 0xffff0000, v14
	v_pk_fma_f32 v[180:181], v[180:181], v[180:181], v[182:183]
	v_and_b32_e32 v183, 0xffff0000, v15
	v_lshlrev_b32_e32 v182, 16, v15
	v_lshlrev_b32_e32 v184, 16, v14
	v_mov_b32_e32 v188, v185
	v_mov_b32_e32 v189, v183
	v_mov_b32_e32 v186, v184
	v_mov_b32_e32 v187, v182
	v_pk_mul_f32 v[188:189], v[188:189], v[188:189]
	v_and_b32_e32 v201, 0xffff0000, v10
	v_pk_fma_f32 v[186:187], v[186:187], v[186:187], v[188:189]
	v_and_b32_e32 v189, 0xffff0000, v12
	v_pk_add_f32 v[186:187], v[186:187], v[186:187] op_sel:[0,1] op_sel_hi:[1,0]
	v_lshlrev_b32_e32 v188, 16, v12
	v_pk_add_f32 v[186:187], v[180:181], v[186:187] op_sel:[1,0] op_sel_hi:[0,1]
	v_pk_add_f32 v[180:181], v[180:181], v[186:187]
	v_and_b32_e32 v187, 0xffff0000, v13
	v_lshlrev_b32_e32 v186, 16, v13
	v_mov_b32_e32 v192, v187
	v_mov_b32_e32 v193, v189
	v_mov_b32_e32 v190, v186
	v_mov_b32_e32 v191, v188
	v_pk_mul_f32 v[192:193], v[192:193], v[192:193]
	v_lshlrev_b32_e32 v200, 16, v10
	v_pk_fma_f32 v[190:191], v[190:191], v[190:191], v[192:193]
	v_and_b32_e32 v193, 0xffff0000, v11
	v_lshlrev_b32_e32 v192, 16, v11
	v_mov_b32_e32 v204, v201
	v_mov_b32_e32 v205, v193
	s_waitcnt vmcnt(5)
	v_lshlrev_b32_e32 v174, 16, v19
	v_mov_b32_e32 v202, v200
	v_mov_b32_e32 v203, v192
	v_pk_mul_f32 v[204:205], v[204:205], v[204:205]
	v_and_b32_e32 v175, 0xffff0000, v19
	v_mul_f32_e32 v62, v174, v174
	v_pk_fma_f32 v[202:203], v[202:203], v[202:203], v[204:205]
	s_waitcnt vmcnt(4)
	v_and_b32_e32 v73, 0xffff0000, v24
	v_and_b32_e32 v165, 0xffff0000, v21
	v_pk_fma_f32 v[62:63], v[174:175], v[174:175], v[62:63] op_sel_hi:[1,1,0]
	v_lshlrev_b32_e32 v66, 16, v18
	v_pk_add_f32 v[202:203], v[202:203], v[202:203] op_sel:[0,1] op_sel_hi:[1,0]
	v_lshlrev_b32_e32 v72, 16, v24
	v_lshlrev_b32_e32 v162, 16, v23
	v_and_b32_e32 v163, 0xffff0000, v23
	v_and_b32_e32 v71, 0xffff0000, v22
	v_lshlrev_b32_e32 v164, 16, v21
	v_and_b32_e32 v69, 0xffff0000, v20
	v_and_b32_e32 v67, 0xffff0000, v18
	v_mul_f32_e32 v62, v66, v66
	v_pk_add_f32 v[202:203], v[190:191], v[202:203] op_sel:[1,0] op_sel_hi:[0,1]
	v_mov_b32_e32 v204, v73
	v_mov_b32_e32 v205, v165
	v_pk_mul_f32 v[60:61], v[162:163], v[162:163]
	v_lshlrev_b32_e32 v70, 16, v22
	v_lshlrev_b32_e32 v68, 16, v20
	v_pk_fma_f32 v[64:65], v[66:67], v[66:67], v[62:63] op_sel_hi:[1,1,0]
	v_pk_add_f32 v[190:191], v[190:191], v[202:203]
	v_mov_b32_e32 v202, v72
	v_mov_b32_e32 v203, v164
	v_pk_mul_f32 v[204:205], v[204:205], v[204:205]
	v_mov_b32_e32 v206, v71
	v_mov_b32_e32 v207, v69
	v_lshlrev_b32_e32 v74, 16, v25
	v_and_b32_e32 v75, 0xffff0000, v25
	v_pk_fma_f32 v[202:203], v[202:203], v[202:203], v[204:205]
	v_mov_b32_e32 v204, v70
	v_mov_b32_e32 v205, v68
	v_pk_mul_f32 v[206:207], v[206:207], v[206:207]
	v_mov_b32_e32 v64, v60
	v_mov_b32_e32 v62, v61
	v_pk_mul_f32 v[58:59], v[74:75], v[74:75]
	v_pk_fma_f32 v[204:205], v[204:205], v[204:205], v[206:207]
	v_pk_add_f32 v[60:61], v[64:65], v[62:63]
	v_mov_b32_e32 v62, v58
	v_pk_add_f32 v[60:61], v[204:205], v[60:61]
	v_mov_b32_e32 v63, v180
	v_pk_mov_b32 v[58:59], v[58:59], v[190:191] op_sel:[1,0]
	v_pk_add_f32 v[60:61], v[202:203], v[60:61]
	v_pk_add_f32 v[58:59], v[62:63], v[58:59]
	s_waitcnt vmcnt(2)
	v_and_b32_e32 v207, 0xffff0000, v30
	v_pk_add_f32 v[58:59], v[60:61], v[58:59]
	v_lshlrev_b32_e32 v206, 16, v30
	v_add_f32_e32 v58, v58, v59
	v_mov_b32_e32 v59, v58
	s_nop 1
	v_permlane16_swap_b32_e32 v59, v58
	v_mov_b32_e32 v210, v207
	v_mov_b32_e32 v208, v206
	ds_read_b128 v[104:107], v149
	ds_read_b128 v[76:79], v149 offset:16
	ds_read_b128 v[100:103], v149 offset:128
	ds_read_b128 v[80:83], v149 offset:144
	ds_read_b128 v[96:99], v149 offset:256
	ds_read_b128 v[84:87], v149 offset:272
	ds_read_b128 v[92:95], v149 offset:384
	ds_read_b128 v[88:91], v149 offset:400
	v_and_b32_e32 v217, 0xffff0000, v26
	s_waitcnt lgkmcnt(8)
	v_add_f32_e32 v58, v58, v59
	v_mov_b32_e32 v59, v58
	s_nop 1
	v_permlane32_swap_b32_e32 v59, v58
	v_lshlrev_b32_e32 v216, 16, v26
	v_mov_b32_e32 v220, v217
	v_mov_b32_e32 v218, v216
	s_waitcnt lgkmcnt(0)
	v_add_f32_e32 v58, v58, v59
	v_fmamk_f32 v58, v58, 0x3c000000, v1
	v_rsq_f32_e32 v58, v58
	s_nop 0
	v_mul_f32_e32 v180, 0x3e0293ee, v58
	v_pk_mul_f32 v[58:59], v[180:181], v[200:201] op_sel_hi:[0,1]
	v_pk_mul_f32 v[60:61], v[180:181], v[192:193] op_sel_hi:[0,1]
	v_and_b32_e32 v193, 0xffff0000, v33
	v_and_b32_e32 v201, 0xffff0000, v32
	v_lshlrev_b32_e32 v192, 16, v33
	v_lshlrev_b32_e32 v200, 16, v32
	v_mov_b32_e32 v204, v193
	v_mov_b32_e32 v205, v201
	v_mov_b32_e32 v202, v192
	v_mov_b32_e32 v203, v200
	v_pk_mul_f32 v[204:205], v[204:205], v[204:205]
	v_pk_mul_f32 v[58:59], v[104:105], v[58:59]
	v_pk_fma_f32 v[202:203], v[202:203], v[202:203], v[204:205]
	v_and_b32_e32 v205, 0xffff0000, v31
	v_lshlrev_b32_e32 v204, 16, v31
	v_mov_b32_e32 v211, v205
	v_mov_b32_e32 v209, v204
	v_pk_mul_f32 v[210:211], v[210:211], v[210:211]
	v_pk_mul_f32 v[60:61], v[106:107], v[60:61]
	v_pk_fma_f32 v[208:209], v[208:209], v[208:209], v[210:211]
	v_and_b32_e32 v211, 0xffff0000, v28
	v_pk_add_f32 v[208:209], v[208:209], v[208:209] op_sel:[0,1] op_sel_hi:[1,0]
	v_lshlrev_b32_e32 v210, 16, v28
	v_pk_add_f32 v[208:209], v[202:203], v[208:209] op_sel:[1,0] op_sel_hi:[0,1]
	v_pk_add_f32 v[202:203], v[202:203], v[208:209]
	v_and_b32_e32 v209, 0xffff0000, v29
	v_lshlrev_b32_e32 v208, 16, v29
	v_mov_b32_e32 v214, v209
	v_mov_b32_e32 v215, v211
	v_mov_b32_e32 v212, v208
	v_mov_b32_e32 v213, v210
	v_pk_mul_f32 v[214:215], v[214:215], v[214:215]
	v_cvt_pk_bf16_f32 v58, v58, v59
	v_cvt_pk_bf16_f32 v59, v60, v61
	v_pk_mul_f32 v[60:61], v[180:181], v[188:189] op_sel_hi:[0,1]
	v_pk_mul_f32 v[62:63], v[180:181], v[186:187] op_sel_hi:[0,1]
	v_pk_fma_f32 v[212:213], v[212:213], v[212:213], v[214:215]
	v_and_b32_e32 v215, 0xffff0000, v27
	v_pk_mul_f32 v[60:61], v[76:77], v[60:61]
	v_pk_mul_f32 v[62:63], v[78:79], v[62:63]
	v_lshlrev_b32_e32 v214, 16, v27
	v_mov_b32_e32 v221, v215
	v_cvt_pk_bf16_f32 v60, v60, v61
	v_cvt_pk_bf16_f32 v61, v62, v63
	v_pk_mul_f32 v[62:63], v[180:181], v[184:185] op_sel_hi:[0,1]
	v_pk_mul_f32 v[64:65], v[180:181], v[182:183] op_sel_hi:[0,1]
	v_pk_mul_f32 v[68:69], v[180:181], v[68:69] op_sel_hi:[0,1]
	v_pk_mul_f32 v[164:165], v[180:181], v[164:165] op_sel_hi:[0,1]
	s_waitcnt vmcnt(1)
; #define LAS __attribute__((address_space(3)))
; __device__ __forceinline__ float bf2f(unsigned h) { return __uint_as_float(h << 16); }
; __device__ __forceinline__ unsigned pk2(float lo, float hi) { return pg8::cvt_pk_bf16(lo, hi); }
; __device__ __forceinline__ void dil_run(const Ctx& X, bf16* H, int l, int run) {
;     ...
;         for (int u = 0; u < 2; ++u) {
;             float s = 0.f;
; #pragma unroll
;             for (int ks = 0; ks < 4; ++ks) { const v4u qw = qw_[u][ks];
;                 const float a0 = bf2f(qw.x & 0xffffu), a1 = bf2f(qw.x >> 16), a2 = bf2f(qw.y & 0xffffu), a3 = bf2f(qw.y >> 16), a4 = bf2f(qw.z & 0xffffu), a5 = bf2f(qw.z >> 16), a6 = bf2f(qw.w & 0xffffu), a7 = bf2f(qw.w >> 16);
;                 s += (a0 * a0 + a1 * a1) + (a2 * a2 + a3 * a3) + (a4 * a4 + a5 * a5) + (a6 * a6 + a7 * a7); }
;             s += __shfl_xor(s, 16); s += __shfl_xor(s, 32);
;             const float sc = (0.08838834764831845f * 1.4426950408889634f) * __builtin_amdgcn_rsqf(s * (1.0f / 128.0f) + EPS);
; #pragma unroll
;             for (int ks = 0; ks < 4; ++ks) { const v4u qw = qw_[u][ks]; const f32x4 g0 = *(const LAS f32x4*)(qgl + 32 * ks + 8 * fq), g1 = *(const LAS f32x4*)(qgl + 32 * ks + 8 * fq + 4);
;                 v4u o; o.x = pk2(bf2f(qw.x & 0xffffu) * sc * g0.x, bf2f(qw.x >> 16) * sc * g0.y); o.y = pk2(bf2f(qw.y & 0xffffu) * sc * g0.z, bf2f(qw.y >> 16) * sc * g0.w);
;                 o.z = pk2(bf2f(qw.z & 0xffffu) * sc * g1.x, bf2f(qw.z >> 16) * sc * g1.y); o.w = pk2(bf2f(qw.w & 0xffffu) * sc * g1.z, bf2f(qw.w >> 16) * sc * g1.w);
;                 qf[u][ks] = __builtin_bit_cast(bf16x8, o); }
;         }
;         asm volatile("" : "+v"(qf[0][0]), "+v"(qf[0][1]), "+v"(qf[0][2]), "+v"(qf[0][3]), "+v"(qf[1][0]), "+v"(qf[1][1]), "+v"(qf[1][2]), "+v"(qf[1][3]));
;         __builtin_amdgcn_sched_barrier(0);
;         DaBlk Bn; if (i < 3) { da_blk_load(X, H, I, nb + 2 * I.dn, Bn); da_q_load(X, H, I, nb + I.dn, qw_); }
	v_lshlrev_b32_e32 v184, 16, v35
	v_mov_b32_e32 v219, v214
	v_pk_mul_f32 v[220:221], v[220:221], v[220:221]
	v_pk_mul_f32 v[62:63], v[100:101], v[62:63]
	v_pk_mul_f32 v[64:65], v[102:103], v[64:65]
	v_pk_mul_f32 v[66:67], v[180:181], v[66:67] op_sel_hi:[0,1]
	v_pk_mul_f32 v[174:175], v[180:181], v[174:175] op_sel_hi:[0,1]
	v_pk_mul_f32 v[68:69], v[84:85], v[68:69]
	v_pk_mul_f32 v[164:165], v[86:87], v[164:165]
	v_and_b32_e32 v185, 0xffff0000, v35
	v_mul_f32_e32 v186, v184, v184
	v_pk_fma_f32 v[218:219], v[218:219], v[218:219], v[220:221]
	v_cvt_pk_bf16_f32 v62, v62, v63
	v_cvt_pk_bf16_f32 v63, v64, v65
	v_pk_mul_f32 v[64:65], v[180:181], v[178:179] op_sel_hi:[0,1]
	v_pk_mul_f32 v[176:177], v[180:181], v[176:177] op_sel_hi:[0,1]
	v_pk_mul_f32 v[66:67], v[96:97], v[66:67]
	v_pk_mul_f32 v[174:175], v[98:99], v[174:175]
	v_cvt_pk_bf16_f32 v68, v68, v69
	v_cvt_pk_bf16_f32 v69, v164, v165
	v_pk_mul_f32 v[70:71], v[180:181], v[70:71] op_sel_hi:[0,1]
	v_pk_mul_f32 v[162:163], v[180:181], v[162:163] op_sel_hi:[0,1]
	v_pk_mul_f32 v[72:73], v[180:181], v[72:73] op_sel_hi:[0,1]
	v_pk_mul_f32 v[74:75], v[180:181], v[74:75] op_sel_hi:[0,1]
	s_waitcnt vmcnt(0)
	v_and_b32_e32 v165, 0xffff0000, v40
	v_and_b32_e32 v181, 0xffff0000, v37
	v_pk_fma_f32 v[186:187], v[184:185], v[184:185], v[186:187] op_sel_hi:[1,1,0]
	v_lshlrev_b32_e32 v188, 16, v34
	v_pk_add_f32 v[218:219], v[218:219], v[218:219] op_sel:[0,1] op_sel_hi:[1,0]
	v_pk_mul_f32 v[64:65], v[80:81], v[64:65]
	v_pk_mul_f32 v[176:177], v[82:83], v[176:177]
	v_cvt_pk_bf16_f32 v66, v66, v67
	v_cvt_pk_bf16_f32 v67, v174, v175
	v_lshlrev_b32_e32 v164, 16, v40
	v_lshlrev_b32_e32 v174, 16, v39
	v_and_b32_e32 v175, 0xffff0000, v39
	v_and_b32_e32 v179, 0xffff0000, v38
	v_lshlrev_b32_e32 v180, 16, v37
	v_and_b32_e32 v183, 0xffff0000, v36
	v_and_b32_e32 v189, 0xffff0000, v34
	v_mul_f32_e32 v186, v188, v188
	v_pk_add_f32 v[218:219], v[212:213], v[218:219] op_sel:[1,0] op_sel_hi:[0,1]
	v_mov_b32_e32 v220, v165
	v_mov_b32_e32 v221, v181
	v_cvt_pk_bf16_f32 v64, v64, v65
	v_cvt_pk_bf16_f32 v65, v176, v177
	v_pk_mul_f32 v[70:71], v[92:93], v[70:71]
	v_pk_mul_f32 v[162:163], v[94:95], v[162:163]
	v_pk_mul_f32 v[176:177], v[174:175], v[174:175]
	v_lshlrev_b32_e32 v178, 16, v38
	v_lshlrev_b32_e32 v182, 16, v36
	v_pk_fma_f32 v[190:191], v[188:189], v[188:189], v[186:187] op_sel_hi:[1,1,0]
	v_pk_add_f32 v[212:213], v[212:213], v[218:219]
	v_mov_b32_e32 v218, v164
	v_mov_b32_e32 v219, v180
	v_pk_mul_f32 v[220:221], v[220:221], v[220:221]
	v_mov_b32_e32 v222, v179
	v_mov_b32_e32 v223, v183
	v_cvt_pk_bf16_f32 v70, v70, v71
	v_cvt_pk_bf16_f32 v71, v162, v163
	v_pk_mul_f32 v[72:73], v[88:89], v[72:73]
	v_pk_mul_f32 v[74:75], v[90:91], v[74:75]
	v_lshlrev_b32_e32 v162, 16, v41
	v_and_b32_e32 v163, 0xffff0000, v41
	v_pk_fma_f32 v[218:219], v[218:219], v[218:219], v[220:221]
	v_mov_b32_e32 v220, v178
	v_mov_b32_e32 v221, v182
	v_pk_mul_f32 v[222:223], v[222:223], v[222:223]
	v_mov_b32_e32 v190, v176
	v_mov_b32_e32 v186, v177
	v_cvt_pk_bf16_f32 v72, v72, v73
	v_cvt_pk_bf16_f32 v73, v74, v75
	v_pk_mul_f32 v[74:75], v[162:163], v[162:163]
	v_pk_fma_f32 v[220:221], v[220:221], v[220:221], v[222:223]
	v_pk_add_f32 v[176:177], v[190:191], v[186:187]
	v_mov_b32_e32 v186, v74
	v_pk_add_f32 v[176:177], v[220:221], v[176:177]
	v_mov_b32_e32 v187, v202
	v_pk_mov_b32 v[74:75], v[74:75], v[212:213] op_sel:[1,0]
	v_pk_add_f32 v[176:177], v[218:219], v[176:177]
	v_pk_add_f32 v[74:75], v[186:187], v[74:75]
	s_nop 0
	v_pk_add_f32 v[74:75], v[176:177], v[74:75]
	s_nop 0
	v_add_f32_e32 v74, v74, v75
	v_mov_b32_e32 v75, v74
	s_nop 1
	v_permlane16_swap_b32_e32 v75, v74
	s_waitcnt lgkmcnt(0)
	v_add_f32_e32 v74, v74, v75
	v_mov_b32_e32 v75, v74
	s_nop 1
	v_permlane32_swap_b32_e32 v75, v74
	s_waitcnt lgkmcnt(0)
	v_add_f32_e32 v74, v74, v75
	v_fmamk_f32 v74, v74, 0x3c000000, v1
	v_rsq_f32_e32 v74, v74
	s_nop 0
	v_mul_f32_e32 v176, 0x3e0293ee, v74
	v_pk_mul_f32 v[74:75], v[176:177], v[216:217] op_sel_hi:[0,1]
	v_pk_mul_f32 v[74:75], v[104:105], v[74:75]
	v_pk_mul_f32 v[104:105], v[176:177], v[214:215] op_sel_hi:[0,1]
	v_pk_mul_f32 v[104:105], v[106:107], v[104:105]
	v_cvt_pk_bf16_f32 v74, v74, v75
	v_cvt_pk_bf16_f32 v75, v104, v105
	v_pk_mul_f32 v[104:105], v[176:177], v[210:211] op_sel_hi:[0,1]
	v_pk_mul_f32 v[76:77], v[76:77], v[104:105]
	v_pk_mul_f32 v[104:105], v[176:177], v[208:209] op_sel_hi:[0,1]
	v_pk_mul_f32 v[78:79], v[78:79], v[104:105]
	v_cvt_pk_bf16_f32 v76, v76, v77
	v_cvt_pk_bf16_f32 v77, v78, v79
	v_pk_mul_f32 v[78:79], v[176:177], v[206:207] op_sel_hi:[0,1]
	v_pk_mul_f32 v[78:79], v[100:101], v[78:79]
	v_pk_mul_f32 v[100:101], v[176:177], v[204:205] op_sel_hi:[0,1]
	v_pk_mul_f32 v[100:101], v[102:103], v[100:101]
	v_cvt_pk_bf16_f32 v78, v78, v79
	v_cvt_pk_bf16_f32 v79, v100, v101
	v_pk_mul_f32 v[100:101], v[176:177], v[200:201] op_sel_hi:[0,1]
	v_pk_mul_f32 v[80:81], v[80:81], v[100:101]
	v_pk_mul_f32 v[100:101], v[176:177], v[192:193] op_sel_hi:[0,1]
	v_pk_mul_f32 v[82:83], v[82:83], v[100:101]
	v_cvt_pk_bf16_f32 v80, v80, v81
	v_cvt_pk_bf16_f32 v81, v82, v83
	v_pk_mul_f32 v[82:83], v[176:177], v[188:189] op_sel_hi:[0,1]
	v_pk_mul_f32 v[82:83], v[96:97], v[82:83]
	v_pk_mul_f32 v[96:97], v[176:177], v[184:185] op_sel_hi:[0,1]
	v_pk_mul_f32 v[96:97], v[98:99], v[96:97]
	v_cvt_pk_bf16_f32 v82, v82, v83
	v_cvt_pk_bf16_f32 v83, v96, v97
	v_pk_mul_f32 v[96:97], v[176:177], v[182:183] op_sel_hi:[0,1]
	v_pk_mul_f32 v[84:85], v[84:85], v[96:97]
	v_pk_mul_f32 v[96:97], v[176:177], v[180:181] op_sel_hi:[0,1]
	v_pk_mul_f32 v[86:87], v[86:87], v[96:97]
	v_cvt_pk_bf16_f32 v84, v84, v85
	v_cvt_pk_bf16_f32 v85, v86, v87
	v_pk_mul_f32 v[86:87], v[176:177], v[178:179] op_sel_hi:[0,1]
	v_pk_mul_f32 v[86:87], v[92:93], v[86:87]
	v_pk_mul_f32 v[92:93], v[176:177], v[174:175] op_sel_hi:[0,1]
	v_pk_mul_f32 v[92:93], v[94:95], v[92:93]
	v_cvt_pk_bf16_f32 v86, v86, v87
	v_cvt_pk_bf16_f32 v87, v92, v93
	v_pk_mul_f32 v[92:93], v[176:177], v[164:165] op_sel_hi:[0,1]
	v_pk_mul_f32 v[88:89], v[88:89], v[92:93]
	v_pk_mul_f32 v[92:93], v[176:177], v[162:163] op_sel_hi:[0,1]
	v_pk_mul_f32 v[90:91], v[90:91], v[92:93]
	v_cvt_pk_bf16_f32 v88, v88, v89
	v_cvt_pk_bf16_f32 v89, v90, v91
	s_cmp_lg_u32 s31, 1
	s_cselect_b64 s[0:1], -1, 0
	s_cmp_eq_u32 s31, 1
	s_cbranch_scc1 .LBB0_275
; __device__ __forceinline__ void da_blk_load(const Ctx& X, const bf16* H, const DaRun& I, int kb, DaBlk& R) {
;     const bool ok = kb >= 0 && kb < I.nbper; const size_t mb = (size_t)I.b * SEQ; const int kcol = I.qcol + 512, vcol = I.qcol + 1024;
; #pragma unroll
;     for (int p = 0; p < 2; ++p) { const int r = (X.tid >> 4) + 32 * p, c8 = X.tid & 15; R.kw[p] = (v4u){0u, 0u, 0u, 0u}; R.vw[p] = (v4u){0u, 0u, 0u, 0u};
;         if (ok) { const size_t mr = mb + (size_t)(I.rho * (SEQ / I.dil) + 64 * kb + r); R.kw[p] = *(const v4u*)hptr(H, mr, kcol + 8 * c8); R.vw[p] = *(const v4u*)hptr(H, mr, vcol + 8 * c8); } }
; }
	s_add_i32 s48, s71, s75
	s_cmp_gt_i32 s48, -1
	s_cselect_b64 s[16:17], -1, 0
	s_cmp_lt_i32 s48, s69
	s_cselect_b64 s[48:49], -1, 0
	s_and_b64 s[16:17], s[16:17], s[48:49]
	s_andn2_b64 vcc, exec, s[16:17]
	s_cbranch_vccnz .LBB0_273
	v_add_u32_e32 v10, s30, v168
	v_ashrrev_i32_e32 v11, 31, v10
	v_lshlrev_b64 v[12:13], 8, v[10:11]
	v_add_u32_e32 v10, 32, v10
	v_ashrrev_i32_e32 v11, 31, v10
	v_lshl_add_u64 v[12:13], v[12:13], 0, s[4:5]
	v_lshlrev_b64 v[10:11], 8, v[10:11]
	v_lshl_add_u64 v[14:15], v[120:121], 0, v[12:13]
	v_lshl_add_u64 v[12:13], v[122:123], 0, v[12:13]
	v_lshl_add_u64 v[10:11], v[10:11], 0, s[4:5]
	global_load_dwordx4 v[42:45], v[14:15], off
	global_load_dwordx4 v[46:49], v[12:13], off
	v_lshl_add_u64 v[12:13], v[120:121], 0, v[10:11]
	v_lshl_add_u64 v[10:11], v[122:123], 0, v[10:11]
	global_load_dwordx4 v[50:53], v[12:13], off
	global_load_dwordx4 v[54:57], v[10:11], off
	s_branch .LBB0_274

; #define LAS __attribute__((address_space(3)))
; #define SP_END(bit) do { if (PROBE_MASK >> 16) { const unsigned long long t1_ = __builtin_amdgcn_s_memrealtime(); if (PROBE_MASK & (1 << (bit))) { const unsigned long long dt_ = t1_ - sp0_; while (__builtin_amdgcn_s_memrealtime() - t1_ < dt_) __builtin_amdgcn_s_sleep(2); } sp0_ = __builtin_amdgcn_s_memrealtime(); } } while (0)
; __device__ __forceinline__ unsigned pk2(float lo, float hi) { return pg8::cvt_pk_bf16(lo, hi); }
; __device__ __forceinline__ void dil_run(const Ctx& X, bf16* H, int l, int run) {
;     ...
;                 for (int j = 0; j < 4; ++j) { p[j] = __builtin_amdgcn_exp2f(acc[u][j]); lloc[u] += p[j]; }
;                 v2u w; w.x = pk2(p[0], p[1]); w.y = pk2(p[2], p[3]); *(LAS v2u*)(P + (32 * qh + 16 * u + fr) * 400 + (48 * kq + 16 * t + 4 * fq) * 2) = w; } }
;         SP_END(17);
; #pragma unroll
;         for (int u = 0; u < 2; ++u) { lloc[u] += __shfl_xor(lloc[u], 16); lloc[u] += __shfl_xor(lloc[u], 32); if (fq == 0) lx[kq * 64 + 32 * qh + 16 * u + fr] = lloc[u]; }
.LBB0_287:
	v_add_f32_e32 v64, 0, v97
	v_add_f32_e32 v64, v98, v64
	v_add_f32_e32 v64, v99, v64
	v_add_f32_e32 v64, v100, v64
	v_add_f32_e32 v64, v64, v106
	v_add_f32_e32 v64, v94, v64
	v_add_f32_e32 v64, v95, v64
	v_add_f32_e32 v64, v107, v64
	v_add_f32_e32 v64, v64, v65
	v_add_f32_e32 v62, v62, v64
	v_add_f32_e32 v62, v63, v62
	v_add_f32_e32 v62, v69, v62
	v_mov_b32_e32 v63, v62
	s_nop 1
	v_permlane16_swap_b32_e32 v63, v62
	v_exp_f32_e32 v60, v60
	v_exp_f32_e32 v58, v58
	v_exp_f32_e32 v59, v59
	v_exp_f32_e32 v61, v61
	s_waitcnt lgkmcnt(0)
	v_add_f32_e32 v62, v62, v63
	v_mov_b32_e32 v63, v62
	s_nop 1
	v_permlane32_swap_b32_e32 v63, v62
	v_cvt_pk_bf16_f32 v64, v60, v58
	v_cvt_pk_bf16_f32 v65, v59, v61
	ds_write_b64 v154, v[64:65] offset:6464
	s_and_saveexec_b64 s[16:17], s[46:47]
	s_cbranch_execz .LBB0_289
	s_waitcnt lgkmcnt(1)
	v_add_f32_e32 v62, v62, v63
	ds_write_b32 v137, v62
.LBB0_289:
	s_or_b64 exec, exec, s[16:17]
	v_add_f32_e32 v62, 0, v101
	v_add_f32_e32 v62, v102, v62
	v_add_f32_e32 v62, v103, v62
	v_add_f32_e32 v62, v104, v62
	v_add_f32_e32 v62, v62, v92
	v_add_f32_e32 v62, v90, v62
	v_add_f32_e32 v62, v91, v62
	v_add_f32_e32 v62, v93, v62
	v_add_f32_e32 v60, v62, v60
	v_add_f32_e32 v58, v58, v60
	v_add_f32_e32 v58, v59, v58
	v_add_f32_e32 v58, v61, v58
	v_mov_b32_e32 v59, v58
	s_nop 1
	v_permlane16_swap_b32_e32 v59, v58
	s_waitcnt lgkmcnt(0)
	v_add_f32_e32 v58, v58, v59
	v_mov_b32_e32 v59, v58
	s_nop 1
	v_permlane32_swap_b32_e32 v59, v58
	s_and_saveexec_b64 s[16:17], s[46:47]
	s_cbranch_execz .LBB0_291
	s_waitcnt lgkmcnt(0)
	v_add_f32_e32 v58, v58, v59
	ds_write_b32 v137, v58 offset:64

; #define LAS __attribute__((address_space(3)))
; __device__ __forceinline__ float bf2f(unsigned h) { return __uint_as_float(h << 16); }
; __device__ __forceinline__ unsigned pk2(float lo, float hi) { return pg8::cvt_pk_bf16(lo, hi); }
; __device__ __forceinline__ void da_blk_stage(const Ctx& X, const f32x4 g0, const f32x4 g1, int kb, const DaBlk& R) {
;     const lptr KN = X.lds + DA_KN, VT = X.lds + DA_VT; const int slot = ((kb % 3) + 3) % 3;
; #pragma unroll
;     for (int p = 0; p < 2; ++p) { const int row = slot * 64 + (X.tid >> 4) + 32 * p, c8 = X.tid & 15; const v4u kw = R.kw[p], vw = R.vw[p];
;         float f[8]; f[0] = bf2f(kw.x & 0xffffu); f[1] = bf2f(kw.x >> 16); f[2] = bf2f(kw.y & 0xffffu); f[3] = bf2f(kw.y >> 16); f[4] = bf2f(kw.z & 0xffffu); f[5] = bf2f(kw.z >> 16); f[6] = bf2f(kw.w & 0xffffu); f[7] = bf2f(kw.w >> 16);
;         float s = 0.f;
; #pragma unroll
;         for (int e = 0; e < 8; ++e) s += f[e] * f[e];
;         s += __shfl_xor(s, 1); s += __shfl_xor(s, 2); s += __shfl_xor(s, 4); s += __shfl_xor(s, 8);
;         const float sc = __builtin_amdgcn_rsqf(s * (1.0f / 128.0f) + EPS);
;         v4u o; o.x = pk2(f[0] * sc * g0.x, f[1] * sc * g0.y); o.y = pk2(f[2] * sc * g0.z, f[3] * sc * g0.w); o.z = pk2(f[4] * sc * g1.x, f[5] * sc * g1.y); o.w = pk2(f[6] * sc * g1.z, f[7] * sc * g1.w);
;         *(LAS v4u*)(KN + row * 272 + c8 * 16) = o;
;         LAS unsigned short* d = (LAS unsigned short*)(VT + (8 * c8) * 400 + (row ^ (8 * (c8 & 7))) * 2);
;         d[0] = (unsigned short)vw.x; d[200] = (unsigned short)(vw.x >> 16); d[400] = (unsigned short)vw.y; d[600] = (unsigned short)(vw.y >> 16);
;         d[800] = (unsigned short)vw.z; d[1000] = (unsigned short)(vw.z >> 16); d[1200] = (unsigned short)vw.w; d[1400] = (unsigned short)(vw.w >> 16); }
; }
; __device__ __forceinline__ void dil_run(const Ctx& X, bf16* H, int l, int run) {
;     ...
;         for (int p = 0; p < 2; ++p) { const int idx = X.tid + NTHR * p, row = idx >> 4, c8 = idx & 15; *(v4u*)hptr(H, (size_t)b * SEQ + (size_t)(rho * Ls + 64 * nb + row), qcol + 8 * c8) = *(const LAS v4u*)(P + row * 272 + c8 * 16); }
.LBB0_293:
	s_or_b64 exec, exec, s[16:17]
	s_waitcnt lgkmcnt(0)
	s_barrier
	ds_read_b128 v[58:61], v152
	v_add_u32_e32 v62, s30, v171
	v_ashrrev_i32_e32 v63, 31, v62
	v_lshl_add_u64 v[62:63], s[14:15], 0, v[62:63]
	v_lshlrev_b64 v[62:63], 8, v[62:63]
	v_lshl_add_u64 v[62:63], v[114:115], 0, v[62:63]
	s_waitcnt lgkmcnt(0)
	global_store_dwordx4 v[62:63], v[58:61], off
	ds_read_b128 v[58:61], v153
	v_add_u32_e32 v62, s30, v170
	v_ashrrev_i32_e32 v63, 31, v62
	v_lshl_add_u64 v[62:63], s[14:15], 0, v[62:63]
	v_lshlrev_b64 v[62:63], 8, v[62:63]
	v_lshl_add_u64 v[62:63], v[114:115], 0, v[62:63]
	s_andn2_b64 vcc, exec, s[0:1]
	s_waitcnt lgkmcnt(0)
	global_store_dwordx4 v[62:63], v[58:61], off
	s_cbranch_vccnz .LBB0_269
	s_waitcnt vmcnt(13)
	v_lshlrev_b32_e32 v70, 16, v42
	v_and_b32_e32 v71, 0xffff0000, v42
	v_lshlrev_b32_e32 v66, 16, v43
	v_and_b32_e32 v67, 0xffff0000, v43
	v_pk_mul_f32 v[72:73], v[70:71], v[70:71]
	v_pk_mul_f32 v[68:69], v[66:67], v[66:67]
	v_add_f32_e32 v72, v72, v73
	v_lshlrev_b32_e32 v60, 16, v44
	v_and_b32_e32 v61, 0xffff0000, v44
	v_add_f32_e32 v68, v68, v72
	v_pk_mul_f32 v[64:65], v[60:61], v[60:61]
	v_add_f32_e32 v68, v69, v68
	v_lshlrev_b32_e32 v62, 16, v45
	v_and_b32_e32 v63, 0xffff0000, v45
	v_add_f32_e32 v64, v64, v68
	v_pk_mul_f32 v[58:59], v[62:63], v[62:63]
	v_add_f32_e32 v64, v65, v64
	v_add_f32_e32 v58, v58, v64
	v_add_f32_e32 v58, v59, v58
	s_add_i32 s0, s71, s75
	s_mul_hi_i32 s1, s0, 0x55555556
	s_lshr_b32 s16, s1, 31
	s_add_i32 s1, s1, s16
	s_waitcnt lgkmcnt(0)
	s_nop 1
	v_add_f32_dpp v58, v58, v58 quad_perm:[1,0,3,2] row_mask:0xf bank_mask:0xf
	s_mul_i32 s1, s1, 3
	s_sub_i32 s0, s0, s1
	s_lshl_b32 s1, s0, 6
	s_add_i32 s16, s1, 0xc0
	s_waitcnt lgkmcnt(0)
	s_nop 1
	v_add_f32_dpp v58, v58, v58 quad_perm:[2,3,0,1] row_mask:0xf bank_mask:0xf
	s_cmp_lt_i32 s0, 0
	s_cselect_b32 s0, s16, s1
	v_add_u32_e32 v74, s0, v129
	s_waitcnt vmcnt(11)
	v_lshlrev_b32_e32 v72, 16, v50
	s_waitcnt lgkmcnt(0)
	s_nop 1
	v_add_f32_dpp v58, v58, v58 row_half_mirror row_mask:0xf bank_mask:0xf
	v_and_b32_e32 v73, 0xffff0000, v50
	v_lshlrev_b32_e32 v68, 16, v51
	v_and_b32_e32 v69, 0xffff0000, v51
	s_waitcnt lgkmcnt(0)
	s_nop 1
	v_add_f32_dpp v58, v58, v58 row_mirror row_mask:0xf bank_mask:0xf
	v_fmamk_f32 v58, v58, 0x3c000000, v1
	v_rsq_f32_e32 v64, v58
	s_nop 0
	v_pk_mul_f32 v[58:59], v[64:65], v[70:71] op_sel_hi:[0,1]
	v_pk_mul_f32 v[66:67], v[64:65], v[66:67] op_sel_hi:[0,1]
	v_pk_mul_f32 v[60:61], v[64:65], v[60:61] op_sel_hi:[0,1]
	v_pk_mul_f32 v[62:63], v[64:65], v[62:63] op_sel_hi:[0,1]
	v_pk_mul_f32 v[58:59], v[2:3], v[58:59]
	v_pk_mul_f32 v[66:67], v[4:5], v[66:67]
	v_pk_mul_f32 v[60:61], v[6:7], v[60:61]
	v_pk_mul_f32 v[62:63], v[8:9], v[62:63]
	v_cvt_pk_bf16_f32 v58, v58, v59
	v_cvt_pk_bf16_f32 v59, v66, v67
	v_cvt_pk_bf16_f32 v60, v60, v61
	v_cvt_pk_bf16_f32 v61, v62, v63
	v_mad_u64_u32 v[62:63], s[0:1], v74, s27, v[112:113]
	ds_write_b128 v62, v[58:61]
	v_xor_b32_e32 v58, v74, v132
	v_add_u32_e32 v63, 32, v74
	v_pk_mul_f32 v[74:75], v[72:73], v[72:73]
	v_pk_mul_f32 v[70:71], v[68:69], v[68:69]
	v_add_f32_e32 v74, v74, v75
	v_lshlrev_b32_e32 v60, 16, v52
	v_and_b32_e32 v61, 0xffff0000, v52
	v_add_f32_e32 v70, v70, v74
	v_pk_mul_f32 v[66:67], v[60:61], v[60:61]
	v_add_f32_e32 v70, v71, v70
	v_lshl_add_u32 v58, v58, 1, v131
	v_lshlrev_b32_e32 v64, 16, v53
	v_and_b32_e32 v65, 0xffff0000, v53
	v_add_f32_e32 v66, v66, v70
	ds_write_b16 v58, v46 offset:52224
	ds_write_b16_d16_hi v58, v46 offset:52624
	ds_write_b16 v58, v47 offset:53024
	ds_write_b16_d16_hi v58, v47 offset:53424
	ds_write_b16 v58, v48 offset:53824
	ds_write_b16_d16_hi v58, v48 offset:54224
	ds_write_b16 v58, v49 offset:54624
	ds_write_b16_d16_hi v58, v49 offset:55024
	v_pk_mul_f32 v[58:59], v[64:65], v[64:65]
	v_add_f32_e32 v66, v67, v66
	v_add_f32_e32 v58, v58, v66
	v_add_f32_e32 v58, v59, v58
	s_waitcnt lgkmcnt(0)
	s_nop 1
	v_add_f32_dpp v58, v58, v58 quad_perm:[1,0,3,2] row_mask:0xf bank_mask:0xf
	s_waitcnt lgkmcnt(0)
	s_nop 1
	v_add_f32_dpp v58, v58, v58 quad_perm:[2,3,0,1] row_mask:0xf bank_mask:0xf
	s_waitcnt lgkmcnt(0)
	s_nop 1
	v_add_f32_dpp v58, v58, v58 row_half_mirror row_mask:0xf bank_mask:0xf
	s_waitcnt lgkmcnt(0)
	s_nop 1
	v_add_f32_dpp v58, v58, v58 row_mirror row_mask:0xf bank_mask:0xf
	v_fmamk_f32 v58, v58, 0x3c000000, v1
	v_rsq_f32_e32 v66, v58
	s_nop 0
	v_pk_mul_f32 v[58:59], v[66:67], v[72:73] op_sel_hi:[0,1]
	v_pk_mul_f32 v[68:69], v[66:67], v[68:69] op_sel_hi:[0,1]
	v_pk_mul_f32 v[60:61], v[66:67], v[60:61] op_sel_hi:[0,1]
	v_pk_mul_f32 v[64:65], v[66:67], v[64:65] op_sel_hi:[0,1]
	v_pk_mul_f32 v[58:59], v[2:3], v[58:59]
	v_pk_mul_f32 v[68:69], v[4:5], v[68:69]
	v_pk_mul_f32 v[60:61], v[6:7], v[60:61]
	v_pk_mul_f32 v[64:65], v[8:9], v[64:65]
	v_cvt_pk_bf16_f32 v58, v58, v59
	v_cvt_pk_bf16_f32 v59, v68, v69
	v_cvt_pk_bf16_f32 v60, v60, v61
	v_cvt_pk_bf16_f32 v61, v64, v65
	ds_write_b128 v62, v[58:61] offset:8704
	v_xor_b32_e32 v58, v63, v132
	v_lshl_add_u32 v58, v58, 1, v131
	s_waitcnt vmcnt(10)
	ds_write_b16 v58, v54 offset:52224
	ds_write_b16_d16_hi v58, v54 offset:52624
	ds_write_b16 v58, v55 offset:53024
	ds_write_b16_d16_hi v58, v55 offset:53424
	ds_write_b16 v58, v56 offset:53824
	ds_write_b16_d16_hi v58, v56 offset:54224
	ds_write_b16 v58, v57 offset:54624
	ds_write_b16_d16_hi v58, v57 offset:55024
	s_branch .LBB0_269
